# group B: P0 cvt back after the barrier (shorter softmax phase)
# baseline (speedup 1.0000x reference)
; #define LAS __attribute__((address_space(3)))
; DI void diff_core(unsigned char* smem, const u16* qptr, const u16* kbase, const u16* vtbase, int vld,
;                   int ntb, int ntw, int nvalid, int ks0, const float* lut, int qpos, bool active, bool grpB,
;                   f32x16 (&O)[4], float& l_out) {
;     ...
;   auto pv = [&](int slot) {
;     if (grpB) __builtin_amdgcn_s_setprio(2); else __builtin_amdgcn_s_setprio(1);
;     const LAS unsigned char* b = lds + slot * D_SLOT;
;     bf16x8 va[4], vb[4];
; #pragma unroll
;     for (int tt = 0; tt < 4; ++tt) va[tt] = *reinterpret_cast<const LAS bf16x8*>(b + voff[0] + tt * 32 * 128);
; #pragma unroll
;     for (int tt = 0; tt < 4; ++tt) vb[tt] = *reinterpret_cast<const LAS bf16x8*>(b + voff[1] + tt * 32 * 128);
;     {
;       const bf16x8 pf = __builtin_bit_cast(bf16x8, P[0]);
; #pragma unroll
;       for (int tt = 0; tt < 4; ++tt) O[tt] = MFMA(va[tt], pf, O[tt]);
;     }
; #pragma unroll
;     for (int tt = 0; tt < 4; ++tt) va[tt] = *reinterpret_cast<const LAS bf16x8*>(b + voff[2] + tt * 32 * 128);
;     {
;       const bf16x8 pf = __builtin_bit_cast(bf16x8, P[1]);
; #pragma unroll
;       for (int tt = 0; tt < 4; ++tt) O[tt] = MFMA(vb[tt], pf, O[tt]);
;     }
; #pragma unroll
;     for (int tt = 0; tt < 4; ++tt) vb[tt] = *reinterpret_cast<const LAS bf16x8*>(b + voff[3] + tt * 32 * 128);
;     {
;       const bf16x8 pf = __builtin_bit_cast(bf16x8, P[2]);
; #pragma unroll
;       for (int tt = 0; tt < 4; ++tt) O[tt] = MFMA(va[tt], pf, O[tt]);
;     }
;     {
;       const bf16x8 pf = __builtin_bit_cast(bf16x8, P[3]);
; #pragma unroll
;       for (int tt = 0; tt < 4; ++tt) O[tt] = MFMA(vb[tt], pf, O[tt]);
;     }
;     __builtin_amdgcn_sched_group_barrier(0x100, 8, 0);
;     __builtin_amdgcn_sched_group_barrier(0x008, 4, 0);
;     __builtin_amdgcn_sched_group_barrier(0x100, 4, 0);
;     __builtin_amdgcn_sched_group_barrier(0x008, 4, 0);
;     __builtin_amdgcn_sched_group_barrier(0x100, 4, 0);
;     __builtin_amdgcn_sched_group_barrier(0x008, 8, 0);
;     __builtin_amdgcn_s_setprio(0);
;   };
;     ...
;     for (int t = 0; t <= ntb; ++t) {
;       const bool act_t = active && (t < ntw);
;       { const int tn = t + 2; dma(tn < tlast ? tn : tlast, tn & 3); }
;       if (act_t) softmax(t);
;       asm volatile("s_waitcnt vmcnt(4)" ::: "memory");
;       D_BAR;
;       if (act_t) pv(t & 3);
.LBB0_384:
	s_waitcnt vmcnt(4)
	s_barrier
	s_andn2_b64 vcc, exec, s[0:1]
	s_cbranch_vccnz .LBB0_386
	s_setprio 2
	v_cvt_pk_bf16_f32 v144, v80, v81
	v_cvt_pk_bf16_f32 v145, v82, v83
	v_cvt_pk_bf16_f32 v146, v84, v85
	v_cvt_pk_bf16_f32 v147, v86, v87
	v_add_f32_e32 v250, v81, v80
	v_add_f32_e32 v250, v82, v250
	s_waitcnt lgkmcnt(0)
	v_mfma_f32_32x32x16_bf16 v[48:63], v[200:203], v[144:147], v[48:63]
	v_cvt_pk_bf16_f32 v148, v88, v89
	v_add_f32_e32 v250, v83, v250
	v_add_f32_e32 v250, v84, v250
	v_add_u32_e32 v97, s100, v186
	ds_read_b128 v[98:101], v97 offset:16384
	ds_read_b128 v[102:105], v97 offset:20480
	ds_read_b128 v[106:109], v97 offset:24576
	ds_read_b128 v[110:113], v97 offset:28672
	v_mfma_f32_32x32x16_bf16 v[32:47], v[204:207], v[144:147], v[32:47]
	v_cvt_pk_bf16_f32 v149, v90, v91
	v_add_f32_e32 v250, v85, v250
	v_add_f32_e32 v250, v86, v250
	v_add_u32_e32 v126, s100, v184
	ds_read_b128 v[114:117], v126 offset:16384
	ds_read_b128 v[118:121], v126 offset:20480
	ds_read_b128 v[122:125], v126 offset:24576
	ds_read_b128 v[196:199], v126 offset:28672
	v_mfma_f32_32x32x16_bf16 v[16:31], v[208:211], v[144:147], v[16:31]
	v_cvt_pk_bf16_f32 v150, v92, v93
	v_add_f32_e32 v250, v87, v250
	v_add_f32_e32 v250, v88, v250
	v_mfma_f32_32x32x16_bf16 v[0:15], v[212:215], v[144:147], v[0:15]
	v_cvt_pk_bf16_f32 v151, v94, v95
	v_add_f32_e32 v250, v89, v250
	v_add_f32_e32 v250, v90, v250
	v_mfma_f32_32x32x16_bf16 v[48:63], v[216:219], v[148:151], v[48:63]
	v_cvt_pk_bf16_f32 v152, v64, v65
	v_add_f32_e32 v250, v91, v250
	v_add_f32_e32 v250, v92, v250
	v_mfma_f32_32x32x16_bf16 v[32:47], v[220:223], v[148:151], v[32:47]
	v_cvt_pk_bf16_f32 v153, v66, v67
	v_add_f32_e32 v250, v93, v250
	v_add_f32_e32 v250, v94, v250
	v_mfma_f32_32x32x16_bf16 v[16:31], v[224:227], v[148:151], v[16:31]
	v_cvt_pk_bf16_f32 v154, v68, v69
	v_add_f32_e32 v250, v95, v250
	v_add_f32_e32 v250, v64, v250
	v_mfma_f32_32x32x16_bf16 v[0:15], v[228:231], v[148:151], v[0:15]
	v_cvt_pk_bf16_f32 v155, v70, v71
	v_add_f32_e32 v250, v65, v250
	v_add_f32_e32 v250, v66, v250
	v_add_u32_e32 v97, s101, v177
	ds_read_b128 v[200:203], v97
	ds_read_b128 v[204:207], v97 offset:8192
	v_add_u32_e32 v126, s101, v178
	ds_read_b128 v[208:211], v126
	ds_read_b128 v[212:215], v126 offset:8192
	s_waitcnt lgkmcnt(8)
	v_mfma_f32_32x32x16_bf16 v[48:63], v[98:101], v[152:155], v[48:63]
	v_cvt_pk_bf16_f32 v156, v72, v73
	v_add_f32_e32 v250, v67, v250
	v_add_f32_e32 v250, v68, v250
	v_mfma_f32_32x32x16_bf16 v[32:47], v[102:105], v[152:155], v[32:47]
	v_cvt_pk_bf16_f32 v157, v74, v75
	v_add_f32_e32 v250, v69, v250
	v_add_f32_e32 v250, v70, v250
	v_mfma_f32_32x32x16_bf16 v[16:31], v[106:109], v[152:155], v[16:31]
	v_cvt_pk_bf16_f32 v158, v76, v77
	v_add_f32_e32 v250, v71, v250
	v_add_f32_e32 v250, v72, v250
	v_mfma_f32_32x32x16_bf16 v[0:15], v[110:113], v[152:155], v[0:15]
	v_cvt_pk_bf16_f32 v159, v78, v79
	v_add_f32_e32 v250, v73, v250
	v_add_f32_e32 v250, v74, v250
	v_add_u32_e32 v97, s101, v179
	ds_read_b128 v[216:219], v97
	ds_read_b128 v[220:223], v97 offset:8192
	v_add_u32_e32 v126, s101, v180
	ds_read_b128 v[224:227], v126
	ds_read_b128 v[228:231], v126 offset:8192
	s_waitcnt lgkmcnt(8)
	v_mfma_f32_32x32x16_bf16 v[48:63], v[114:117], v[156:159], v[48:63]
	v_add_f32_e32 v250, v75, v250
	v_add_f32_e32 v250, v76, v250
	v_mfma_f32_32x32x16_bf16 v[32:47], v[118:121], v[156:159], v[32:47]
	v_add_f32_e32 v250, v77, v250
	v_add_f32_e32 v250, v78, v250
	v_mfma_f32_32x32x16_bf16 v[16:31], v[122:125], v[156:159], v[16:31]
	v_add_f32_e32 v250, v79, v250
	v_mfma_f32_32x32x16_bf16 v[0:15], v[196:199], v[156:159], v[0:15]
	v_add_f32_e32 v181, v181, v250
	s_setprio 0
